# attention item epilogue: permlane32_swap pairs + dwordx4 stores (8 dwordx2 -> 4 dwordx4 per lane)
# baseline (speedup 1.0000x reference)
; __device__ __forceinline__ float shx32(float v, int lane) { return __int_as_float(__builtin_amdgcn_ds_bpermute((lane ^ 32) << 2, __float_as_int(v))); }
; __device__ __forceinline__ unsigned pk_bf16(float lo, float hi) { unsigned r; asm("v_cvt_pk_bf16_f32 %0, %1, %2" : "=v"(r) : "v"(lo), "v"(hi)); return r; }
; template <int MODE>
; __device__ __forceinline__ void attn_phase(const Args& a, bool do_ctx, LAS unsigned char* lds, const int wid_s) {
;     ...
;         const float ltot = lsum + shx32(lsum, lane);
;         const float inv = 1.0f / ltot;
;         bf16_t* orow = AC + (size_t)qrow * 1024 + h * 64;
; #pragma unroll
;         for (int db = 0; db < 2; ++db)
; #pragma unroll
;             for (int g = 0; g < 4; ++g) {
;                 u32x2 o = {pk_bf16(ot[db][4 * g + 0] * inv, ot[db][4 * g + 1] * inv), pk_bf16(ot[db][4 * g + 2] * inv, ot[db][4 * g + 3] * inv)};
;                 if (MODE == 0 || (o[0] == 0x12345678u && o[1] == 0x9abcdef1u)) *(u32x2*)(orow + db * 32 + 8 * g + 4 * hf) = o;
;             }
.LBB0_421:
	ds_bpermute_b32 v34, v163, v167
	v_lshlrev_b64 v[32:33], 11, v[144:145]
	s_lshl_b32 s76, s26, 1
	v_mov_b32_e32 v143, v201
	s_add_i32 s24, s24, 1
	s_waitcnt lgkmcnt(0)
	v_add_f32_e32 v34, v167, v34
	v_div_scale_f32 v35, s[2:3], v34, v34, 1.0
	v_rcp_f32_e32 v36, v35
	v_div_scale_f32 v37, vcc, 1.0, v34, 1.0
	v_readlane_b32 s2, v248, 2
	v_fma_f32 v38, -v35, v36, 1.0
	v_fmac_f32_e32 v36, v38, v36
	v_mul_f32_e32 v38, v37, v36
	v_fma_f32 v39, -v35, v38, v37
	v_fmac_f32_e32 v38, v39, v36
	v_fma_f32 v35, -v35, v38, v37
	v_div_fmas_f32 v35, v35, v36, v38
	v_readlane_b32 s3, v248, 3
	v_div_fixup_f32 v34, v35, v34, 1.0
	s_nop 1
	v_lshl_add_u64 v[32:33], s[2:3], 0, v[32:33]
	v_lshl_add_u64 v[32:33], v[32:33], 0, s[76:77]
	v_lshl_add_u64 v[32:33], v[32:33], 0, v[142:143]
	v_lshl_add_u64 v[32:33], v[32:33], 0, v[142:143]
	v_mul_f32_e32 v0, v0, v34
	v_mul_f32_e32 v1, v1, v34
	v_cvt_pk_bf16_f32 v0, v0, v1
	v_mul_f32_e32 v1, v2, v34
	v_mul_f32_e32 v2, v3, v34
	v_cvt_pk_bf16_f32 v1, v1, v2
	v_mul_f32_e32 v2, v4, v34
	v_mul_f32_e32 v3, v5, v34
	v_cvt_pk_bf16_f32 v2, v2, v3
	v_mul_f32_e32 v3, v6, v34
	v_mul_f32_e32 v4, v7, v34
	v_cvt_pk_bf16_f32 v3, v3, v4
	s_nop 1
	v_permlane32_swap_b32_e32 v0, v2
	v_permlane32_swap_b32_e32 v1, v3
	global_store_dwordx4 v[32:33], v[0:3], off
	v_mul_f32_e32 v8, v8, v34
	v_mul_f32_e32 v9, v9, v34
	v_cvt_pk_bf16_f32 v8, v8, v9
	v_mul_f32_e32 v9, v10, v34
	v_mul_f32_e32 v10, v11, v34
	v_cvt_pk_bf16_f32 v9, v9, v10
	v_mul_f32_e32 v10, v12, v34
	v_mul_f32_e32 v11, v13, v34
	v_cvt_pk_bf16_f32 v10, v10, v11
	v_mul_f32_e32 v11, v14, v34
	v_mul_f32_e32 v12, v15, v34
	v_cvt_pk_bf16_f32 v11, v11, v12
	s_nop 1
	v_permlane32_swap_b32_e32 v8, v10
	v_permlane32_swap_b32_e32 v9, v11
	global_store_dwordx4 v[32:33], v[8:11], off offset:32
	v_mul_f32_e32 v16, v16, v34
	v_mul_f32_e32 v17, v17, v34
	v_cvt_pk_bf16_f32 v16, v16, v17
	v_mul_f32_e32 v17, v18, v34
	v_mul_f32_e32 v18, v19, v34
	v_cvt_pk_bf16_f32 v17, v17, v18
	v_mul_f32_e32 v18, v20, v34
	v_mul_f32_e32 v19, v21, v34
	v_cvt_pk_bf16_f32 v18, v18, v19
	v_mul_f32_e32 v19, v22, v34
	v_mul_f32_e32 v20, v23, v34
	v_cvt_pk_bf16_f32 v19, v19, v20
	s_nop 1
	v_permlane32_swap_b32_e32 v16, v18
	v_permlane32_swap_b32_e32 v17, v19
	global_store_dwordx4 v[32:33], v[16:19], off offset:64
	v_mul_f32_e32 v24, v24, v34
	v_mul_f32_e32 v25, v25, v34
	v_cvt_pk_bf16_f32 v24, v24, v25
	v_mul_f32_e32 v25, v26, v34
	v_mul_f32_e32 v26, v27, v34
	v_cvt_pk_bf16_f32 v25, v25, v26
	v_mul_f32_e32 v26, v28, v34
	v_mul_f32_e32 v27, v29, v34
	v_cvt_pk_bf16_f32 v26, v26, v27
	v_mul_f32_e32 v27, v30, v34
	v_mul_f32_e32 v28, v31, v34
	v_cvt_pk_bf16_f32 v27, v27, v28
	s_nop 1
	v_permlane32_swap_b32_e32 v24, v26
	v_permlane32_swap_b32_e32 v25, v27
	global_store_dwordx4 v[32:33], v[24:27], off offset:96
	s_mov_b64 s[8:9], 0
